# conv: first two items per workgroup assigned statically (2*blockIdx, +1; no start-up atomic), further tickets drawn dynamically with offset 2*gridDim; on top of the conv counted-wait fixes
# baseline (speedup 1.0000x reference)
.LBB0_483:
	v_mov_b32_e32 v0, v215
	v_mov_b32_e32 v1, 0
	v_readfirstlane_b32 s3, v0
	v_and_b32_e32 v80, 63, v0
	s_and_b32 s0, s3, 0xc0
	v_or_b32_e32 v81, s0, v80
	v_lshlrev_b32_e32 v0, 3, v81
	s_waitcnt lgkmcnt(0)
	v_lshl_add_u64 v[2:3], s[22:23], 0, v[0:1]
	s_movk_i32 s0, 0x1000
	v_add_co_u32_e32 v4, vcc, s0, v2
	s_movk_i32 s0, 0x2000
	s_nop 0
	v_addc_co_u32_e32 v5, vcc, 0, v3, vcc
	v_add_co_u32_e32 v6, vcc, s0, v2
	s_movk_i32 s0, 0x3000
	s_nop 0
	v_addc_co_u32_e32 v7, vcc, 0, v3, vcc
	v_add_co_u32_e32 v8, vcc, s0, v2
	s_movk_i32 s0, 0x4000
	s_nop 0
	v_addc_co_u32_e32 v9, vcc, 0, v3, vcc
	v_add_co_u32_e32 v10, vcc, s0, v2
	s_movk_i32 s0, 0x5000
	s_nop 0
	v_addc_co_u32_e32 v11, vcc, 0, v3, vcc
	v_add_co_u32_e32 v12, vcc, s0, v2
	s_movk_i32 s0, 0x6000
	s_nop 0
	v_addc_co_u32_e32 v13, vcc, 0, v3, vcc
	v_add_co_u32_e32 v14, vcc, s0, v2
	s_movk_i32 s0, 0x7000
	s_nop 0
	v_addc_co_u32_e32 v15, vcc, 0, v3, vcc
	global_load_dwordx2 v[16:17], v[6:7], off
	global_load_dwordx2 v[18:19], v[6:7], off offset:2048
	global_load_dwordx2 v[20:21], v[10:11], off offset:-4096
	global_load_dwordx2 v[22:23], v[10:11], off
	global_load_dwordx2 v[24:25], v[10:11], off offset:2048
	global_load_dwordx2 v[26:27], v[14:15], off offset:-4096
	global_load_dwordx2 v[28:29], v[14:15], off
	global_load_dwordx2 v[30:31], v[14:15], off offset:2048
	v_add_co_u32_e32 v10, vcc, s0, v2
	s_mov_b32 s0, 0x8000
	s_nop 0
	v_addc_co_u32_e32 v11, vcc, 0, v3, vcc
	v_add_co_u32_e32 v14, vcc, s0, v2
	s_mov_b32 s0, 0x9000
	s_nop 0
	v_addc_co_u32_e32 v15, vcc, 0, v3, vcc
	global_load_dwordx2 v[32:33], v[4:5], off offset:2048
	global_load_dwordx2 v[34:35], v[8:9], off offset:2048
	global_load_dwordx2 v[36:37], v[12:13], off offset:2048
	global_load_dwordx2 v[38:39], v[10:11], off offset:2048
	v_add_co_u32_e32 v4, vcc, s0, v2
	s_mov_b32 s0, 0xa000
	s_nop 0
	v_addc_co_u32_e32 v5, vcc, 0, v3, vcc
	v_add_co_u32_e32 v8, vcc, s0, v2
	s_mov_b32 s0, 0xb000
	s_nop 0
	v_addc_co_u32_e32 v9, vcc, 0, v3, vcc
	v_add_co_u32_e32 v10, vcc, s0, v2
	s_mov_b32 s0, 0xc000
	s_nop 0
	v_addc_co_u32_e32 v11, vcc, 0, v3, vcc
	v_add_co_u32_e32 v12, vcc, s0, v2
	s_mov_b32 s0, 0xd000
	s_nop 0
	v_addc_co_u32_e32 v13, vcc, 0, v3, vcc
	global_load_dwordx2 v[40:41], v[14:15], off offset:-4096
	global_load_dwordx2 v[42:43], v[14:15], off
	global_load_dwordx2 v[44:45], v[14:15], off offset:2048
	global_load_dwordx2 v[46:47], v[8:9], off offset:-4096
	global_load_dwordx2 v[48:49], v[8:9], off
	global_load_dwordx2 v[50:51], v[8:9], off offset:2048
	global_load_dwordx2 v[52:53], v[12:13], off offset:-4096
	global_load_dwordx2 v[54:55], v[12:13], off
	v_add_co_u32_e32 v8, vcc, s0, v2
	s_mov_b32 s0, 0xe000
	s_nop 0
	v_addc_co_u32_e32 v9, vcc, 0, v3, vcc
	v_add_co_u32_e32 v14, vcc, s0, v2
	v_lshlrev_b32_e32 v82, 5, v80
	s_nop 0
	v_addc_co_u32_e32 v15, vcc, 0, v3, vcc
	v_add_co_u32_e32 v2, vcc, 0xf000, v2
	global_load_dwordx2 v[56:57], v[12:13], off offset:2048
	global_load_dwordx2 v[58:59], v[14:15], off offset:-4096
	global_load_dwordx2 v[60:61], v[14:15], off
	global_load_dwordx2 v[62:63], v[14:15], off offset:2048
	v_addc_co_u32_e32 v3, vcc, 0, v3, vcc
	global_load_dwordx2 v[64:65], v[4:5], off offset:2048
	global_load_dwordx2 v[66:67], v[10:11], off offset:2048
	global_load_dwordx2 v[68:69], v[8:9], off offset:2048
	global_load_dwordx2 v[70:71], v[2:3], off
	global_load_dwordx2 v[72:73], v0, s[22:23]
	global_load_dwordx2 v[74:75], v0, s[22:23] offset:2048
	global_load_dwordx2 v[76:77], v[6:7], off offset:-4096
	global_load_dwordx2 v[78:79], v0, s[24:25]
	s_nop 0
	global_load_dwordx4 v[0:3], v82, s[26:27] offset:16
	global_load_dwordx4 v[4:7], v82, s[28:29] offset:16
	global_load_dwordx4 v[8:11], v82, s[26:27]
	global_load_dwordx4 v[12:15], v82, s[28:29]
	s_ashr_i32 s10, s3, 6
	v_lshlrev_b32_e32 v84, 3, v80
	v_or_b32_e32 v80, s10, v80
	v_lshlrev_b32_e32 v101, 1, v81
	v_cmp_eq_u32_e64 s[4:5], 0, v80
	s_and_saveexec_b64 s[0:1], s[4:5]
	v_readlane_b32 s68, v254, 0
	v_readlane_b32 s76, v254, 19
	v_readlane_b32 s69, v254, 1
	v_readlane_b32 s70, v254, 2
	v_readlane_b32 s71, v254, 3
	v_readlane_b32 s72, v254, 4
	v_readlane_b32 s73, v254, 5
	v_readlane_b32 s74, v254, 6
	v_readlane_b32 s75, v254, 7
	v_readlane_b32 s77, v254, 20
	s_cbranch_execz .LBB0_489
	s_mov_b64 s[8:9], exec
	v_mbcnt_lo_u32_b32 v80, s8, 0
	v_mbcnt_hi_u32_b32 v80, s9, v80
	v_cmp_eq_u32_e32 vcc, 0, v80
	s_and_saveexec_b64 s[6:7], vcc
	s_cbranch_execz .LBB0_486
	v_readlane_b32 s2, v254, 25
	s_lshl_b32 s2, s2, 1
	v_mov_b32_e32 v81, s2
.LBB0_486:
	s_or_b64 exec, exec, s[6:7]
	v_readfirstlane_b32 s2, v81
	s_nop 1
	v_add_u32_e32 v80, s2, v80
	s_add_i32 s2, 0, 0x23f40
	v_mov_b32_e32 v81, s2
	ds_write_b32 v81, v80
	v_add_u32_e32 v80, 1, v80
	ds_write_b32 v81, v80 offset:4

.Lconv_pf_join:
	v_lshlrev_b32_e32 v168, 16, v80
	v_and_b32_e32 v169, 0xffff0000, v80
	v_mov_b32_e32 v80, s20
	v_pk_fma_f32 v[166:167], v[70:71], v[168:169], v[166:167]
	ds_write2st64_b64 v102, v[150:151], v[148:149] offset0:64 offset1:68
	ds_write2st64_b64 v102, v[152:153], v[146:147] offset0:72 offset1:76
	ds_write2st64_b64 v102, v[154:155], v[144:145] offset0:80 offset1:84
	ds_write2st64_b64 v102, v[156:157], v[142:143] offset0:88 offset1:92
	ds_write2st64_b64 v102, v[158:159], v[160:161] offset0:96 offset1:100
	ds_write2st64_b64 v102, v[140:141], v[138:139] offset0:104 offset1:108
	ds_write2st64_b64 v102, v[162:163], v[136:137] offset0:112 offset1:116
	ds_write2st64_b64 v102, v[164:165], v[166:167] offset0:120 offset1:124
	s_and_saveexec_b64 s[98:99], s[4:5]
	s_cbranch_execz .Lconv_tk
	s_waitcnt vmcnt(46)
	v_mov_b32_e32 v231, s20
	s_nop 0
	v_readlane_b32 s100, v254, 19
	s_lshl_b32 s100, s100, 1
	v_add_u32_e32 v230, s100, v230
	ds_write_b32 v231, v230
